# code placement: heads of the five large GEMM K loops aligned to 64 bytes (s_nop fill outside the loops)
# baseline (speedup 1.0000x reference)
; template <class Epi, class Sched>
; __device__ __forceinline__ void gemm_phase(LAS unsigned char* lds, const Gemm g, const Sched& S, const Epi& E) {
;     ...
;     for (;;) {
;         const bool has_next = S.next(ui + 1, nxt);
;         const char* nA = has_next ? (const char*)g.A + (size_t)nxt.pm * tA + (size_t)nxt.k0 * 2 : cA; const char* nB = has_next ? (const char*)g.Bt + (size_t)nxt.pn * tB + (size_t)nxt.k0 * 2 : cB;
;         const int nt = cur.nt;
;         for (int t = 0; t < nt; t += 2) {
;     ...
;             bf16x8 zf = {0, 0, 0, 0, 0, 0, 0, 0}; asm volatile("" : "+v"(zf));
; #pragma unroll
;             for (int a = 0; a < 2; ++a)
; #pragma unroll
;                 for (int b = 0; b < 2; ++b)
; #pragma unroll
;                     for (int m = 0; m < 4; ++m)
; #pragma unroll
;                         for (int n = 0; n < 2; ++n) acc[a][b][m][n] = __builtin_amdgcn_mfma_f32_16x16x32_bf16(zf, zf, (f32x4){0.f, 0.f, 0.f, 0.f}, 0, 0, 0);
.LBB0_258:
	s_ashr_i32 s17, s16, 31
	s_lshl_b64 s[18:19], s[16:17], 20
	v_readlane_b32 s20, v253, 34
	v_readlane_b32 s21, v253, 35
	s_add_u32 s18, s20, s18
	s_addc_u32 s19, s21, s19
	s_and_b64 s[20:21], s[0:1], exec
	s_cselect_b32 s17, s19, s3
	s_cselect_b32 s26, s18, s2
	s_ashr_i32 s15, s14, 31
	s_lshl_b64 s[20:21], s[14:15], 20
	s_add_u32 s20, s30, s20
	s_addc_u32 s21, s31, s21
	s_and_b64 s[24:25], s[0:1], exec
	s_cselect_b32 s15, s21, s23
	s_cselect_b32 s27, s20, s22
	s_add_u32 s2, s2, 0x80080
	s_addc_u32 s3, s3, 0
	s_add_u32 s28, s22, 0x100
	s_waitcnt vmcnt(12)
	v_mov_b64_e32 v[2:3], v[206:207]
	v_mov_b64_e32 v[4:5], v[208:209]
	v_mov_b64_e32 v[6:7], v[202:203]
	v_mov_b64_e32 v[8:9], v[204:205]
	v_mov_b64_e32 v[10:11], v[198:199]
	v_mov_b64_e32 v[12:13], v[200:201]
	v_mov_b64_e32 v[14:15], v[194:195]
	v_mov_b64_e32 v[16:17], v[196:197]
	v_mov_b64_e32 v[18:19], v[206:207]
	v_mov_b64_e32 v[20:21], v[208:209]
	v_mov_b64_e32 v[22:23], v[202:203]
	v_mov_b64_e32 v[24:25], v[204:205]
	v_mov_b64_e32 v[26:27], v[198:199]
	v_mov_b64_e32 v[28:29], v[200:201]
	v_mov_b64_e32 v[30:31], v[194:195]
	v_mov_b64_e32 v[32:33], v[196:197]
	v_mov_b64_e32 v[34:35], v[206:207]
	v_mov_b64_e32 v[36:37], v[208:209]
	v_mov_b64_e32 v[38:39], v[202:203]
	v_mov_b64_e32 v[40:41], v[204:205]
	v_mov_b64_e32 v[50:51], v[198:199]
	v_mov_b64_e32 v[52:53], v[200:201]
	v_mov_b64_e32 v[54:55], v[194:195]
	v_mov_b64_e32 v[56:57], v[196:197]
	v_mov_b64_e32 v[66:67], v[206:207]
	v_mov_b64_e32 v[68:69], v[208:209]
	v_mov_b64_e32 v[70:71], v[202:203]
	v_mov_b64_e32 v[72:73], v[204:205]
	v_mov_b64_e32 v[74:75], v[198:199]
	v_mov_b64_e32 v[76:77], v[200:201]
	v_mov_b64_e32 v[78:79], v[194:195]
	v_mov_b64_e32 v[80:81], v[196:197]
	v_mov_b64_e32 v[82:83], v[206:207]
	v_mov_b64_e32 v[84:85], v[208:209]
	v_mov_b64_e32 v[86:87], v[202:203]
	v_mov_b64_e32 v[88:89], v[204:205]
	v_mov_b64_e32 v[90:91], v[198:199]
	v_mov_b64_e32 v[92:93], v[200:201]
	v_mov_b64_e32 v[94:95], v[194:195]
	v_mov_b64_e32 v[96:97], v[196:197]
	v_mov_b64_e32 v[100:101], v[206:207]
	v_mov_b64_e32 v[102:103], v[208:209]
	v_mov_b64_e32 v[104:105], v[202:203]
	v_mov_b64_e32 v[106:107], v[204:205]
	v_mov_b64_e32 v[108:109], v[198:199]
	v_mov_b64_e32 v[110:111], v[200:201]
	v_mov_b64_e32 v[112:113], v[194:195]
	v_mov_b64_e32 v[114:115], v[196:197]
	v_mov_b64_e32 v[116:117], v[206:207]
	v_mov_b64_e32 v[118:119], v[208:209]
	v_mov_b64_e32 v[120:121], v[202:203]
	v_mov_b64_e32 v[122:123], v[204:205]
	v_mov_b64_e32 v[124:125], v[198:199]
	v_mov_b64_e32 v[126:127], v[200:201]
	v_mov_b64_e32 v[128:129], v[194:195]
	v_mov_b64_e32 v[130:131], v[196:197]
	v_mov_b64_e32 v[132:133], v[206:207]
	v_mov_b64_e32 v[134:135], v[208:209]
	v_mov_b64_e32 v[136:137], v[202:203]
	v_mov_b64_e32 v[138:139], v[204:205]
	v_mov_b64_e32 v[140:141], v[198:199]
	v_mov_b64_e32 v[142:143], v[200:201]
	v_mov_b64_e32 v[144:145], v[194:195]
	v_mov_b64_e32 v[146:147], v[196:197]
	s_addc_u32 s29, s23, 0
	s_mov_b32 s46, -2
	.p2alignl 6, 3212836864

; template <class Epi, class Sched>
; __device__ __forceinline__ void gemm_phase(LAS unsigned char* lds, const Gemm g, const Sched& S, const Epi& E) {
;     ...
;     for (;;) {
;         const bool has_next = S.next(ui + 1, nxt);
;         const char* nA = has_next ? (const char*)g.A + (size_t)nxt.pm * tA + (size_t)nxt.k0 * 2 : cA; const char* nB = has_next ? (const char*)g.Bt + (size_t)nxt.pn * tB + (size_t)nxt.k0 * 2 : cB;
;         const int nt = cur.nt;
;         for (int t = 0; t < nt; t += 2) {
;             const bool last = (t == nt - 2);
;             const char* a1 = cA + (size_t)(t + 1) * kstepA;
;             const char* a2 = last ? nA : cA + (size_t)(t + 2) * kstepA; const char* b2 = last ? nB : cB + (size_t)(t + 2) * kstep;
;             const char* a3 = a2 + kstepA; const char* b3 = b2 + kstep;
.LBB0_707:
	s_ashr_i32 s13, s12, 31
	s_lshl_b64 s[16:17], s[12:13], 20
	s_add_u32 s9, s33, s16
	s_addc_u32 s13, s54, s17
	s_ashr_i32 s15, s14, 31
	s_lshl_b64 s[18:19], s[14:15], 1
	s_add_u32 s16, s9, s18
	s_addc_u32 s17, s13, s19
	s_and_b64 s[22:23], s[0:1], exec
	s_cselect_b32 s13, s17, s3
	s_cselect_b32 s15, s16, s2
	s_ashr_i32 s9, s8, 31
	s_lshl_b64 s[22:23], s[8:9], 20
	s_add_u32 s9, s26, s22
	s_addc_u32 s22, s27, s23
	s_add_u32 s18, s9, s18
	s_addc_u32 s19, s22, s19
	s_and_b64 s[22:23], s[0:1], exec
	s_cselect_b32 s9, s19, s21
	s_cselect_b32 s42, s18, s20
	s_add_i32 s43, s24, -2
	s_add_u32 s2, s2, 0x80080
	s_addc_u32 s3, s3, 0
	s_add_u32 s46, s20, 0x100
	s_addc_u32 s47, s21, 0
	s_mov_b32 s20, 0
	.p2alignl 6, 3212836864

; template <class Epi, class Sched>
; __device__ __forceinline__ void gemm_phase(LAS unsigned char* lds, const Gemm g, const Sched& S, const Epi& E) {
;     ...
;     for (;;) {
;         const bool has_next = S.next(ui + 1, nxt);
;         const char* nA = has_next ? (const char*)g.A + (size_t)nxt.pm * tA + (size_t)nxt.k0 * 2 : cA; const char* nB = has_next ? (const char*)g.Bt + (size_t)nxt.pn * tB + (size_t)nxt.k0 * 2 : cB;
;         const int nt = cur.nt;
;         for (int t = 0; t < nt; t += 2) {
;     ...
;             bf16x8 zf = {0, 0, 0, 0, 0, 0, 0, 0}; asm volatile("" : "+v"(zf));
; #pragma unroll
;             for (int a = 0; a < 2; ++a)
; #pragma unroll
;                 for (int b = 0; b < 2; ++b)
; #pragma unroll
;                     for (int m = 0; m < 4; ++m)
; #pragma unroll
;                         for (int n = 0; n < 2; ++n) acc[a][b][m][n] = __builtin_amdgcn_mfma_f32_16x16x32_bf16(zf, zf, (f32x4){0.f, 0.f, 0.f, 0.f}, 0, 0, 0);
.LBB0_841:
	s_ashr_i32 s19, s18, 31
	s_lshl_b64 s[20:21], s[18:19], 20
	v_readlane_b32 s22, v253, 34
	v_readlane_b32 s23, v253, 35
	s_add_u32 s20, s22, s20
	s_addc_u32 s21, s23, s21
	s_and_b64 s[22:23], s[74:75], exec
	s_cselect_b32 s19, s21, s25
	s_cselect_b32 s46, s20, s24
	s_ashr_i32 s17, s16, 31
	s_lshl_b64 s[22:23], s[16:17], 20
	s_add_u32 s22, s30, s22
	s_addc_u32 s23, s31, s23
	s_and_b64 s[26:27], s[74:75], exec
	s_cselect_b32 s17, s23, s3
	s_cselect_b32 s47, s22, s2
	s_add_u32 s48, s2, 0x100
	v_mov_b64_e32 v[8:9], v[4:5]
	v_mov_b64_e32 v[20:21], v[4:5]
	v_mov_b64_e32 v[24:25], v[4:5]
	v_mov_b64_e32 v[36:37], v[4:5]
	v_mov_b64_e32 v[40:41], v[4:5]
	v_mov_b64_e32 v[52:53], v[4:5]
	v_mov_b64_e32 v[56:57], v[4:5]
	v_mov_b64_e32 v[12:13], v[4:5]
	v_mov_b64_e32 v[16:17], v[4:5]
	v_mov_b64_e32 v[28:29], v[4:5]
	v_mov_b64_e32 v[32:33], v[4:5]
	v_mov_b64_e32 v[44:45], v[4:5]
	v_mov_b64_e32 v[48:49], v[4:5]
	v_mov_b64_e32 v[60:61], v[4:5]
	v_mov_b64_e32 v[64:65], v[4:5]
	v_mov_b64_e32 v[68:69], v[4:5]
	v_mov_b64_e32 v[72:73], v[4:5]
	v_mov_b64_e32 v[84:85], v[4:5]
	v_mov_b64_e32 v[88:89], v[4:5]
	v_mov_b64_e32 v[102:103], v[4:5]
	v_mov_b64_e32 v[106:107], v[4:5]
	v_mov_b64_e32 v[118:119], v[4:5]
	v_mov_b64_e32 v[122:123], v[4:5]
	v_mov_b64_e32 v[76:77], v[4:5]
	v_mov_b64_e32 v[80:81], v[4:5]
	v_mov_b64_e32 v[92:93], v[4:5]
	v_mov_b64_e32 v[96:97], v[4:5]
	v_mov_b64_e32 v[110:111], v[4:5]
	v_mov_b64_e32 v[114:115], v[4:5]
	v_mov_b64_e32 v[126:127], v[4:5]
	v_mov_b64_e32 v[130:131], v[4:5]
	s_addc_u32 s50, s3, 0
	s_mov_b32 s52, -2
	v_mov_b64_e32 v[6:7], v[2:3]
	v_mov_b64_e32 v[18:19], v[2:3]
	v_mov_b64_e32 v[22:23], v[2:3]
	v_mov_b64_e32 v[34:35], v[2:3]
	v_mov_b64_e32 v[38:39], v[2:3]
	v_mov_b64_e32 v[50:51], v[2:3]
	v_mov_b64_e32 v[54:55], v[2:3]
	v_mov_b64_e32 v[10:11], v[2:3]
	v_mov_b64_e32 v[14:15], v[2:3]
	v_mov_b64_e32 v[26:27], v[2:3]
	v_mov_b64_e32 v[30:31], v[2:3]
	v_mov_b64_e32 v[42:43], v[2:3]
	v_mov_b64_e32 v[46:47], v[2:3]
	v_mov_b64_e32 v[58:59], v[2:3]
	v_mov_b64_e32 v[62:63], v[2:3]
	v_mov_b64_e32 v[66:67], v[2:3]
	v_mov_b64_e32 v[70:71], v[2:3]
	v_mov_b64_e32 v[82:83], v[2:3]
	v_mov_b64_e32 v[86:87], v[2:3]
	v_mov_b64_e32 v[100:101], v[2:3]
	v_mov_b64_e32 v[104:105], v[2:3]
	v_mov_b64_e32 v[116:117], v[2:3]
	v_mov_b64_e32 v[120:121], v[2:3]
	v_mov_b64_e32 v[74:75], v[2:3]
	v_mov_b64_e32 v[78:79], v[2:3]
	v_mov_b64_e32 v[90:91], v[2:3]
	v_mov_b64_e32 v[94:95], v[2:3]
	v_mov_b64_e32 v[108:109], v[2:3]
	v_mov_b64_e32 v[112:113], v[2:3]
	v_mov_b64_e32 v[124:125], v[2:3]
	v_mov_b64_e32 v[128:129], v[2:3]
	s_mov_b64 s[96:97], 0x100
	.p2alignl 6, 3212836864

; template <class Epi, class Sched>
; __device__ __forceinline__ void gemm_phase(LAS unsigned char* lds, const Gemm g, const Sched& S, const Epi& E) {
;     ...
;     for (;;) {
;         const bool has_next = S.next(ui + 1, nxt);
;         const char* nA = has_next ? (const char*)g.A + (size_t)nxt.pm * tA + (size_t)nxt.k0 * 2 : cA; const char* nB = has_next ? (const char*)g.Bt + (size_t)nxt.pn * tB + (size_t)nxt.k0 * 2 : cB;
;         const int nt = cur.nt;
;         for (int t = 0; t < nt; t += 2) {
;     ...
;             bf16x8 zf = {0, 0, 0, 0, 0, 0, 0, 0}; asm volatile("" : "+v"(zf));
; #pragma unroll
;             for (int a = 0; a < 2; ++a)
; #pragma unroll
;                 for (int b = 0; b < 2; ++b)
; #pragma unroll
;                     for (int m = 0; m < 4; ++m)
; #pragma unroll
;                         for (int n = 0; n < 2; ++n) acc[a][b][m][n] = __builtin_amdgcn_mfma_f32_16x16x32_bf16(zf, zf, (f32x4){0.f, 0.f, 0.f, 0.f}, 0, 0, 0);
.LBB0_977:
	s_ashr_i32 s9, s8, 31
	s_lshl_b64 s[12:13], s[8:9], 20
	v_readlane_b32 s14, v253, 34
	v_readlane_b32 s15, v253, 35
	s_add_u32 s12, s14, s12
	s_addc_u32 s13, s15, s13
	s_and_b64 s[14:15], s[0:1], exec
	s_cselect_b32 s9, s13, s17
	s_cselect_b32 s36, s12, s16
	s_ashr_i32 s7, s6, 31
	s_lshl_b64 s[14:15], s[6:7], 20
	s_add_u32 s14, s22, s14
	s_addc_u32 s15, s23, s15
	s_and_b64 s[20:21], s[0:1], exec
	s_cselect_b32 s7, s15, s19
	s_cselect_b32 s37, s14, s18
	s_add_u32 s16, s16, 0x80080
	s_addc_u32 s17, s17, 0
	s_add_u32 s38, s18, 0x100
	v_mov_b64_e32 v[8:9], v[4:5]
	v_mov_b64_e32 v[20:21], v[4:5]
	v_mov_b64_e32 v[24:25], v[4:5]
	v_mov_b64_e32 v[36:37], v[4:5]
	v_mov_b64_e32 v[40:41], v[4:5]
	v_mov_b64_e32 v[52:53], v[4:5]
	v_mov_b64_e32 v[56:57], v[4:5]
	v_mov_b64_e32 v[12:13], v[4:5]
	v_mov_b64_e32 v[16:17], v[4:5]
	v_mov_b64_e32 v[28:29], v[4:5]
	v_mov_b64_e32 v[32:33], v[4:5]
	v_mov_b64_e32 v[44:45], v[4:5]
	v_mov_b64_e32 v[48:49], v[4:5]
	v_mov_b64_e32 v[60:61], v[4:5]
	v_mov_b64_e32 v[64:65], v[4:5]
	v_mov_b64_e32 v[68:69], v[4:5]
	v_mov_b64_e32 v[72:73], v[4:5]
	v_mov_b64_e32 v[84:85], v[4:5]
	v_mov_b64_e32 v[88:89], v[4:5]
	v_mov_b64_e32 v[102:103], v[4:5]
	v_mov_b64_e32 v[106:107], v[4:5]
	v_mov_b64_e32 v[118:119], v[4:5]
	v_mov_b64_e32 v[122:123], v[4:5]
	v_mov_b64_e32 v[76:77], v[4:5]
	v_mov_b64_e32 v[80:81], v[4:5]
	v_mov_b64_e32 v[92:93], v[4:5]
	v_mov_b64_e32 v[96:97], v[4:5]
	v_mov_b64_e32 v[110:111], v[4:5]
	v_mov_b64_e32 v[114:115], v[4:5]
	v_mov_b64_e32 v[126:127], v[4:5]
	v_mov_b64_e32 v[130:131], v[4:5]
	s_addc_u32 s39, s19, 0
	s_mov_b32 s40, -2
	v_mov_b64_e32 v[6:7], v[2:3]
	v_mov_b64_e32 v[18:19], v[2:3]
	v_mov_b64_e32 v[22:23], v[2:3]
	v_mov_b64_e32 v[34:35], v[2:3]
	v_mov_b64_e32 v[38:39], v[2:3]
	v_mov_b64_e32 v[50:51], v[2:3]
	v_mov_b64_e32 v[54:55], v[2:3]
	v_mov_b64_e32 v[10:11], v[2:3]
	v_mov_b64_e32 v[14:15], v[2:3]
	v_mov_b64_e32 v[26:27], v[2:3]
	v_mov_b64_e32 v[30:31], v[2:3]
	v_mov_b64_e32 v[42:43], v[2:3]
	v_mov_b64_e32 v[46:47], v[2:3]
	v_mov_b64_e32 v[58:59], v[2:3]
	v_mov_b64_e32 v[62:63], v[2:3]
	v_mov_b64_e32 v[66:67], v[2:3]
	v_mov_b64_e32 v[70:71], v[2:3]
	v_mov_b64_e32 v[82:83], v[2:3]
	v_mov_b64_e32 v[86:87], v[2:3]
	v_mov_b64_e32 v[100:101], v[2:3]
	v_mov_b64_e32 v[104:105], v[2:3]
	v_mov_b64_e32 v[116:117], v[2:3]
	v_mov_b64_e32 v[120:121], v[2:3]
	v_mov_b64_e32 v[74:75], v[2:3]
	v_mov_b64_e32 v[78:79], v[2:3]
	v_mov_b64_e32 v[90:91], v[2:3]
	v_mov_b64_e32 v[94:95], v[2:3]
	v_mov_b64_e32 v[108:109], v[2:3]
	v_mov_b64_e32 v[112:113], v[2:3]
	v_mov_b64_e32 v[124:125], v[2:3]
	v_mov_b64_e32 v[128:129], v[2:3]
	.p2alignl 6, 3212836864

; template <class Epi, class Sched>
; __device__ __forceinline__ void gemm_phase(LAS unsigned char* lds, const Gemm g, const Sched& S, const Epi& E) {
;     ...
;     for (;;) {
;         const bool has_next = S.next(ui + 1, nxt);
;         const char* nA = has_next ? (const char*)g.A + (size_t)nxt.pm * tA + (size_t)nxt.k0 * 2 : cA; const char* nB = has_next ? (const char*)g.Bt + (size_t)nxt.pn * tB + (size_t)nxt.k0 * 2 : cB;
;         const int nt = cur.nt;
;         for (int t = 0; t < nt; t += 2) {
;     ...
;             bf16x8 zf = {0, 0, 0, 0, 0, 0, 0, 0}; asm volatile("" : "+v"(zf));
; #pragma unroll
;             for (int a = 0; a < 2; ++a)
; #pragma unroll
;                 for (int b = 0; b < 2; ++b)
; #pragma unroll
;                     for (int m = 0; m < 4; ++m)
; #pragma unroll
;                         for (int n = 0; n < 2; ++n) acc[a][b][m][n] = __builtin_amdgcn_mfma_f32_16x16x32_bf16(zf, zf, (f32x4){0.f, 0.f, 0.f, 0.f}, 0, 0, 0);
.LBB0_1047:
	s_add_u32 s42, s2, 0x100
	v_mov_b64_e32 v[8:9], v[4:5]
	v_mov_b64_e32 v[20:21], v[4:5]
	v_mov_b64_e32 v[24:25], v[4:5]
	v_mov_b64_e32 v[36:37], v[4:5]
	v_mov_b64_e32 v[40:41], v[4:5]
	v_mov_b64_e32 v[52:53], v[4:5]
	v_mov_b64_e32 v[56:57], v[4:5]
	v_mov_b64_e32 v[12:13], v[4:5]
	v_mov_b64_e32 v[16:17], v[4:5]
	v_mov_b64_e32 v[28:29], v[4:5]
	v_mov_b64_e32 v[32:33], v[4:5]
	v_mov_b64_e32 v[44:45], v[4:5]
	v_mov_b64_e32 v[48:49], v[4:5]
	v_mov_b64_e32 v[60:61], v[4:5]
	v_mov_b64_e32 v[64:65], v[4:5]
	v_mov_b64_e32 v[68:69], v[4:5]
	v_mov_b64_e32 v[72:73], v[4:5]
	v_mov_b64_e32 v[84:85], v[4:5]
	v_mov_b64_e32 v[88:89], v[4:5]
	v_mov_b64_e32 v[102:103], v[4:5]
	v_mov_b64_e32 v[106:107], v[4:5]
	v_mov_b64_e32 v[118:119], v[4:5]
	v_mov_b64_e32 v[122:123], v[4:5]
	v_mov_b64_e32 v[76:77], v[4:5]
	v_mov_b64_e32 v[80:81], v[4:5]
	v_mov_b64_e32 v[92:93], v[4:5]
	v_mov_b64_e32 v[96:97], v[4:5]
	v_mov_b64_e32 v[110:111], v[4:5]
	v_mov_b64_e32 v[114:115], v[4:5]
	v_mov_b64_e32 v[126:127], v[4:5]
	v_mov_b64_e32 v[130:131], v[4:5]
	s_addc_u32 s43, s3, 0
	s_mov_b32 s46, -2
	v_mov_b64_e32 v[6:7], v[2:3]
	v_mov_b64_e32 v[18:19], v[2:3]
	v_mov_b64_e32 v[22:23], v[2:3]
	v_mov_b64_e32 v[34:35], v[2:3]
	v_mov_b64_e32 v[38:39], v[2:3]
	v_mov_b64_e32 v[50:51], v[2:3]
	v_mov_b64_e32 v[54:55], v[2:3]
	v_mov_b64_e32 v[10:11], v[2:3]
	v_mov_b64_e32 v[14:15], v[2:3]
	v_mov_b64_e32 v[26:27], v[2:3]
	v_mov_b64_e32 v[30:31], v[2:3]
	v_mov_b64_e32 v[42:43], v[2:3]
	v_mov_b64_e32 v[46:47], v[2:3]
	v_mov_b64_e32 v[58:59], v[2:3]
	v_mov_b64_e32 v[62:63], v[2:3]
	v_mov_b64_e32 v[66:67], v[2:3]
	v_mov_b64_e32 v[70:71], v[2:3]
	v_mov_b64_e32 v[82:83], v[2:3]
	v_mov_b64_e32 v[86:87], v[2:3]
	v_mov_b64_e32 v[100:101], v[2:3]
	v_mov_b64_e32 v[104:105], v[2:3]
	v_mov_b64_e32 v[116:117], v[2:3]
	v_mov_b64_e32 v[120:121], v[2:3]
	v_mov_b64_e32 v[74:75], v[2:3]
	v_mov_b64_e32 v[78:79], v[2:3]
	v_mov_b64_e32 v[90:91], v[2:3]
	v_mov_b64_e32 v[94:95], v[2:3]
	v_mov_b64_e32 v[108:109], v[2:3]
	v_mov_b64_e32 v[112:113], v[2:3]
	v_mov_b64_e32 v[124:125], v[2:3]
	v_mov_b64_e32 v[128:129], v[2:3]
	.p2alignl 6, 3212836864
